# stack5: stack4 + attention-post row loop unrolled x2 with trip B in free VGPRs: 24 row loads + 8 sub-LN weight loads in flight together
# baseline (speedup 1.0000x reference)
.Lplam_join:
	s_cbranch_scc1 .LBB0_618
	v_lshlrev_b32_e32 v0, 3, v8
	v_and_b32_e32 v12, 0x78, v0
	v_lshlrev_b32_e32 v248, 2, v12
	global_load_dword v0, v248, s[60:61]
	global_load_dword v16, v248, s[60:61] offset:4
	global_load_dword v1, v248, s[60:61] offset:8
	global_load_dword v17, v248, s[60:61] offset:12
	global_load_dword v4, v248, s[60:61] offset:16
	global_load_dword v2, v248, s[60:61] offset:20
	global_load_dword v5, v248, s[60:61] offset:24
	global_load_dword v3, v248, s[60:61] offset:28
	s_lshl_b32 s7, s40, 8
	v_add_f32_e32 v10, s5, v42
	s_lshl_b32 s5, s40, 2
	s_lshl_b32 s6, s40, 6
	s_add_i32 s41, s4, -8
	s_lshl_b32 s4, s4, 4
	s_and_b32 s7, s7, 0x1f00
	s_and_b32 s5, s5, 0x180
	s_and_b32 s6, s6, 0xffffe000
	v_or_b32_e32 v18, s5, v12
	s_add_i32 s4, s4, s7
	v_bfe_u32 v14, v8, 4, 2
	v_lshlrev_b32_e32 v8, 1, v18
	s_add_i32 s4, s4, s6
	v_mov_b32_e32 v11, v10
	v_lshl_add_u64 v[12:13], s[30:31], 0, v[8:9]
	v_or3_b32 v14, v14, s4, 12
	v_lshlrev_b32_e32 v8, 1, v18
.LBB0_617:
	v_add_u32_e32 v6, -12, v14
	v_add_u32_e32 v18, -8, v14
	v_add_u32_e32 v20, -4, v14
	v_ashrrev_i32_e32 v15, 31, v14
	v_ashrrev_i32_e32 v7, 31, v6
	v_ashrrev_i32_e32 v19, 31, v18
	v_ashrrev_i32_e32 v21, 31, v20
	v_lshlrev_b64 v[22:23], 10, v[14:15]
	v_lshlrev_b64 v[32:33], 10, v[6:7]
	v_lshlrev_b64 v[34:35], 10, v[18:19]
	v_lshlrev_b64 v[36:37], 10, v[20:21]
	v_lshlrev_b64 v[24:25], 11, v[14:15]
	v_or_b32_e32 v22, v22, v8
	v_or_b32_e32 v32, v32, v8
	v_or_b32_e32 v34, v34, v8
	v_or_b32_e32 v36, v36, v8
	v_lshlrev_b64 v[26:27], 11, v[6:7]
	v_lshlrev_b64 v[18:19], 11, v[18:19]
	v_lshlrev_b64 v[28:29], 11, v[20:21]
	v_lshl_add_u64 v[6:7], v[12:13], 0, v[24:25]
	v_lshl_add_u64 v[76:77], s[18:19], 0, v[22:23]
	v_lshl_add_u64 v[24:25], s[22:23], 0, v[22:23]
	v_lshl_add_u64 v[30:31], s[48:49], 0, v[22:23]
	v_lshl_add_u64 v[44:45], s[18:19], 0, v[32:33]
	v_lshl_add_u64 v[46:47], s[22:23], 0, v[32:33]
	v_lshl_add_u64 v[48:49], s[48:49], 0, v[32:33]
	v_lshl_add_u64 v[56:57], s[18:19], 0, v[34:35]
	v_lshl_add_u64 v[52:53], s[22:23], 0, v[34:35]
	v_lshl_add_u64 v[60:61], s[48:49], 0, v[34:35]
	v_lshl_add_u64 v[68:69], s[18:19], 0, v[36:37]
	v_lshl_add_u64 v[64:65], s[22:23], 0, v[36:37]
	v_lshl_add_u64 v[22:23], v[12:13], 0, v[26:27]
	v_lshl_add_u64 v[20:21], v[12:13], 0, v[18:19]
	v_lshl_add_u64 v[18:19], v[12:13], 0, v[28:29]
	global_load_dwordx4 v[24:27], v[24:25], off
	v_lshl_add_u64 v[36:37], s[48:49], 0, v[36:37]
	global_load_dwordx4 v[28:31], v[30:31], off
	s_nop 0
	global_load_dwordx4 v[32:35], v[46:47], off
	s_nop 0
	global_load_dwordx4 v[44:47], v[44:45], off
	s_nop 0
	global_load_dwordx4 v[48:51], v[48:49], off
	s_nop 0
	global_load_dwordx4 v[52:55], v[52:53], off
	s_nop 0
	global_load_dwordx4 v[56:59], v[56:57], off
	s_nop 0
	global_load_dwordx4 v[60:63], v[60:61], off
	s_nop 0
	global_load_dwordx4 v[64:67], v[64:65], off
	s_nop 0
	global_load_dwordx4 v[68:71], v[68:69], off
	s_nop 0
	global_load_dwordx4 v[72:75], v[36:37], off
	s_nop 0
	global_load_dwordx4 v[76:79], v[76:77], off
	v_add_u32_e32 v14, 0x80, v14
	v_mov_b32_e32 v134, v14

	v_add_u32_e32 v126, -12, v134
	v_add_u32_e32 v138, -8, v134
	v_add_u32_e32 v140, -4, v134
	v_ashrrev_i32_e32 v135, 31, v134
	v_ashrrev_i32_e32 v127, 31, v126
	v_ashrrev_i32_e32 v139, 31, v138
	v_ashrrev_i32_e32 v141, 31, v140
	v_lshlrev_b64 v[142:143], 10, v[134:135]
	v_lshlrev_b64 v[152:153], 10, v[126:127]
	v_lshlrev_b64 v[154:155], 10, v[138:139]
	v_lshlrev_b64 v[156:157], 10, v[140:141]
	v_lshlrev_b64 v[144:145], 11, v[134:135]
	v_or_b32_e32 v142, v142, v8
	v_or_b32_e32 v152, v152, v8
	v_or_b32_e32 v154, v154, v8
	v_or_b32_e32 v156, v156, v8
	v_lshlrev_b64 v[146:147], 11, v[126:127]
	v_lshlrev_b64 v[138:139], 11, v[138:139]
	v_lshlrev_b64 v[148:149], 11, v[140:141]
	v_lshl_add_u64 v[126:127], v[12:13], 0, v[144:145]
	v_lshl_add_u64 v[196:197], s[18:19], 0, v[142:143]
	v_lshl_add_u64 v[144:145], s[22:23], 0, v[142:143]
	v_lshl_add_u64 v[150:151], s[48:49], 0, v[142:143]
	v_lshl_add_u64 v[164:165], s[18:19], 0, v[152:153]
	v_lshl_add_u64 v[166:167], s[22:23], 0, v[152:153]
	v_lshl_add_u64 v[168:169], s[48:49], 0, v[152:153]
	v_lshl_add_u64 v[176:177], s[18:19], 0, v[154:155]
	v_lshl_add_u64 v[172:173], s[22:23], 0, v[154:155]
	v_lshl_add_u64 v[180:181], s[48:49], 0, v[154:155]
	v_lshl_add_u64 v[188:189], s[18:19], 0, v[156:157]
	v_lshl_add_u64 v[184:185], s[22:23], 0, v[156:157]
	v_lshl_add_u64 v[142:143], v[12:13], 0, v[146:147]
	v_lshl_add_u64 v[140:141], v[12:13], 0, v[138:139]
	v_lshl_add_u64 v[138:139], v[12:13], 0, v[148:149]
	global_load_dwordx4 v[144:147], v[144:145], off
	v_lshl_add_u64 v[156:157], s[48:49], 0, v[156:157]
	global_load_dwordx4 v[148:151], v[150:151], off
	s_nop 0
	global_load_dwordx4 v[152:155], v[166:167], off
	s_nop 0
	global_load_dwordx4 v[164:167], v[164:165], off
	s_nop 0
	global_load_dwordx4 v[168:171], v[168:169], off
	s_nop 0
	global_load_dwordx4 v[172:175], v[172:173], off
	s_nop 0
	global_load_dwordx4 v[176:179], v[176:177], off
	s_nop 0
	global_load_dwordx4 v[180:183], v[180:181], off
	s_nop 0
	global_load_dwordx4 v[184:187], v[184:185], off
	s_nop 0
	global_load_dwordx4 v[188:191], v[188:189], off
	s_nop 0
	global_load_dwordx4 v[192:195], v[156:157], off
	s_nop 0
	global_load_dwordx4 v[196:199], v[196:197], off
	s_waitcnt vmcnt(21)
	v_lshlrev_b32_e32 v88, 16, v32
	v_lshlrev_b32_e32 v89, 16, v33
	s_waitcnt vmcnt(20)
	v_lshlrev_b32_e32 v97, 16, v45
	v_lshlrev_b32_e32 v96, 16, v44
	v_and_b32_e32 v90, 0xffff0000, v32
	v_and_b32_e32 v91, 0xffff0000, v33
	v_lshlrev_b32_e32 v80, 16, v24
	v_lshlrev_b32_e32 v81, 16, v25
	v_lshlrev_b32_e32 v92, 16, v34
	v_and_b32_e32 v94, 0xffff0000, v34
	v_lshlrev_b32_e32 v93, 16, v35
	v_and_b32_e32 v95, 0xffff0000, v35
	v_and_b32_e32 v45, 0xffff0000, v45
	v_and_b32_e32 v44, 0xffff0000, v44
	v_lshlrev_b32_e32 v99, 16, v47
	v_lshlrev_b32_e32 v98, 16, v46
	s_waitcnt vmcnt(18)
	v_lshlrev_b32_e32 v104, 16, v54
	v_and_b32_e32 v54, 0xffff0000, v54
	v_lshlrev_b32_e32 v105, 16, v55
	v_and_b32_e32 v55, 0xffff0000, v55
	s_waitcnt vmcnt(17)
	v_lshlrev_b32_e32 v111, 16, v59
	v_lshlrev_b32_e32 v110, 16, v58
	v_and_b32_e32 v59, 0xffff0000, v59
	v_and_b32_e32 v58, 0xffff0000, v58
	s_waitcnt vmcnt(15)
	v_lshlrev_b32_e32 v114, 16, v64
	v_lshlrev_b32_e32 v115, 16, v65
	v_lshlrev_b32_e32 v116, 16, v66
	v_and_b32_e32 v66, 0xffff0000, v66
	v_lshlrev_b32_e32 v117, 16, v67
	v_and_b32_e32 v67, 0xffff0000, v67
	s_waitcnt vmcnt(14)
	v_lshlrev_b32_e32 v119, 16, v69
	v_lshlrev_b32_e32 v118, 16, v68
	s_waitcnt vmcnt(13)
	v_lshlrev_b32_e32 v33, 16, v73
	v_lshlrev_b32_e32 v32, 16, v72
	v_and_b32_e32 v35, 0xffff0000, v73
	v_and_b32_e32 v34, 0xffff0000, v72
	v_lshlrev_b32_e32 v73, 16, v71
	v_lshlrev_b32_e32 v72, 16, v70
	v_and_b32_e32 v71, 0xffff0000, v71
	v_and_b32_e32 v70, 0xffff0000, v70
	s_waitcnt vmcnt(12)
	v_lshlrev_b32_e32 v123, 16, v77
	v_lshlrev_b32_e32 v122, 16, v76
	v_pk_fma_f32 v[88:89], v[10:11], v[88:89], v[96:97] neg_lo:[1,0,0] neg_hi:[1,0,0]
	v_and_b32_e32 v82, 0xffff0000, v24
	v_and_b32_e32 v83, 0xffff0000, v25
	v_and_b32_e32 v47, 0xffff0000, v47
	v_and_b32_e32 v46, 0xffff0000, v46
	v_lshlrev_b32_e32 v102, 16, v52
	v_lshlrev_b32_e32 v103, 16, v53
	v_lshlrev_b32_e32 v107, 16, v57
	v_lshlrev_b32_e32 v106, 16, v56
	v_and_b32_e32 v64, 0xffff0000, v64
	v_and_b32_e32 v65, 0xffff0000, v65
	v_and_b32_e32 v69, 0xffff0000, v69
	v_and_b32_e32 v68, 0xffff0000, v68
	v_and_b32_e32 v77, 0xffff0000, v77
	v_and_b32_e32 v76, 0xffff0000, v76
	v_pk_fma_f32 v[44:45], v[10:11], v[90:91], v[44:45] neg_lo:[1,0,0] neg_hi:[1,0,0]
	v_pk_fma_f32 v[90:91], v[10:11], v[92:93], v[98:99] neg_lo:[1,0,0] neg_hi:[1,0,0]
	v_pk_fma_f32 v[54:55], v[10:11], v[54:55], v[58:59] neg_lo:[1,0,0] neg_hi:[1,0,0]
	v_pk_fma_f32 v[58:59], v[10:11], v[114:115], v[118:119] neg_lo:[1,0,0] neg_hi:[1,0,0]
	v_pk_fma_f32 v[66:67], v[10:11], v[66:67], v[70:71] neg_lo:[1,0,0] neg_hi:[1,0,0]
	v_pk_fma_f32 v[70:71], v[10:11], v[80:81], v[122:123] neg_lo:[1,0,0] neg_hi:[1,0,0]
	v_pk_mul_f32 v[80:81], v[88:89], v[88:89]
	v_lshlrev_b32_e32 v84, 16, v26
	v_lshlrev_b32_e32 v85, 16, v27
	v_and_b32_e32 v52, 0xffff0000, v52
	v_and_b32_e32 v53, 0xffff0000, v53
	v_and_b32_e32 v57, 0xffff0000, v57
	v_and_b32_e32 v56, 0xffff0000, v56
	v_lshlrev_b32_e32 v125, 16, v79
	v_lshlrev_b32_e32 v124, 16, v78
	v_pk_fma_f32 v[46:47], v[10:11], v[94:95], v[46:47] neg_lo:[1,0,0] neg_hi:[1,0,0]
	v_pk_fma_f32 v[92:93], v[10:11], v[102:103], v[106:107] neg_lo:[1,0,0] neg_hi:[1,0,0]
	v_pk_fma_f32 v[64:65], v[10:11], v[64:65], v[68:69] neg_lo:[1,0,0] neg_hi:[1,0,0]
	v_pk_fma_f32 v[68:69], v[10:11], v[116:117], v[72:73] neg_lo:[1,0,0] neg_hi:[1,0,0]
	v_pk_fma_f32 v[72:73], v[10:11], v[82:83], v[76:77] neg_lo:[1,0,0] neg_hi:[1,0,0]
	v_pk_mul_f32 v[82:83], v[90:91], v[90:91]
	v_pk_mul_f32 v[94:95], v[58:59], v[58:59]
	v_pk_fma_f32 v[80:81], v[44:45], v[44:45], v[80:81]
	v_and_b32_e32 v86, 0xffff0000, v26
	v_and_b32_e32 v87, 0xffff0000, v27
	v_and_b32_e32 v79, 0xffff0000, v79
	v_and_b32_e32 v78, 0xffff0000, v78
	v_pk_fma_f32 v[52:53], v[10:11], v[52:53], v[56:57] neg_lo:[1,0,0] neg_hi:[1,0,0]
	v_pk_fma_f32 v[56:57], v[10:11], v[104:105], v[110:111] neg_lo:[1,0,0] neg_hi:[1,0,0]
	v_pk_fma_f32 v[76:77], v[10:11], v[84:85], v[124:125] neg_lo:[1,0,0] neg_hi:[1,0,0]
	v_pk_mul_f32 v[84:85], v[92:93], v[92:93]
	v_pk_mul_f32 v[96:97], v[68:69], v[68:69]
	v_pk_fma_f32 v[82:83], v[46:47], v[46:47], v[82:83]
	v_pk_fma_f32 v[94:95], v[64:65], v[64:65], v[94:95]
	v_add_f32_e32 v15, v80, v81
	v_pk_fma_f32 v[78:79], v[10:11], v[86:87], v[78:79] neg_lo:[1,0,0] neg_hi:[1,0,0]
	v_pk_mul_f32 v[86:87], v[56:57], v[56:57]
	v_pk_fma_f32 v[84:85], v[52:53], v[52:53], v[84:85]
	v_pk_fma_f32 v[96:97], v[66:67], v[66:67], v[96:97]
	v_add_f32_e32 v80, v94, v95
	v_add_f32_e32 v15, v82, v15
	v_pk_mul_f32 v[98:99], v[70:71], v[70:71]
	v_pk_fma_f32 v[86:87], v[54:55], v[54:55], v[86:87]
	v_add_f32_e32 v43, v84, v85
	v_add_f32_e32 v80, v96, v80
	v_add_f32_e32 v15, v83, v15
	v_pk_mul_f32 v[102:103], v[76:77], v[76:77]
	v_pk_fma_f32 v[98:99], v[72:73], v[72:73], v[98:99]
	v_add_f32_e32 v43, v86, v43
	v_add_f32_e32 v80, v97, v80
	v_add_f32_dpp v15, v15, v15 quad_perm:[1,0,3,2] row_mask:0xf bank_mask:0xf bound_ctrl:1
	v_pk_fma_f32 v[102:103], v[78:79], v[78:79], v[102:103]
	v_add_f32_e32 v81, v98, v99
	v_add_f32_e32 v43, v87, v43
	v_add_f32_dpp v80, v80, v80 quad_perm:[1,0,3,2] row_mask:0xf bank_mask:0xf bound_ctrl:1
	v_add_f32_dpp v15, v15, v15 quad_perm:[2,3,0,1] row_mask:0xf bank_mask:0xf bound_ctrl:1
	v_add_f32_e32 v81, v102, v81
	v_add_f32_dpp v43, v43, v43 quad_perm:[1,0,3,2] row_mask:0xf bank_mask:0xf bound_ctrl:1
	v_add_f32_dpp v80, v80, v80 quad_perm:[2,3,0,1] row_mask:0xf bank_mask:0xf bound_ctrl:1
	v_add_f32_dpp v15, v15, v15 row_half_mirror row_mask:0xf bank_mask:0xf bound_ctrl:1
	v_add_f32_e32 v81, v103, v81
	v_add_f32_dpp v43, v43, v43 quad_perm:[2,3,0,1] row_mask:0xf bank_mask:0xf bound_ctrl:1
	v_add_f32_dpp v80, v80, v80 row_half_mirror row_mask:0xf bank_mask:0xf bound_ctrl:1
	v_add_f32_dpp v15, v15, v15 row_mirror row_mask:0xf bank_mask:0xf bound_ctrl:1
	v_add_f32_dpp v81, v81, v81 quad_perm:[1,0,3,2] row_mask:0xf bank_mask:0xf bound_ctrl:1
	v_add_f32_dpp v43, v43, v43 row_half_mirror row_mask:0xf bank_mask:0xf bound_ctrl:1
	v_add_f32_dpp v80, v80, v80 row_mirror row_mask:0xf bank_mask:0xf bound_ctrl:1
	v_fmamk_f32 v15, v15, 0x3c000000, v39
	v_add_f32_dpp v81, v81, v81 quad_perm:[2,3,0,1] row_mask:0xf bank_mask:0xf bound_ctrl:1
	v_add_f32_dpp v43, v43, v43 row_mirror row_mask:0xf bank_mask:0xf bound_ctrl:1
	v_fmamk_f32 v80, v80, 0x3c000000, v39
	v_mul_f32_e32 v82, 0x4f800000, v15
	v_cmp_gt_f32_e64 s[8:9], s42, v15
	v_add_f32_dpp v81, v81, v81 row_half_mirror row_mask:0xf bank_mask:0xf bound_ctrl:1
	v_fmamk_f32 v43, v43, 0x3c000000, v39
	v_mul_f32_e32 v84, 0x4f800000, v80
	v_cmp_gt_f32_e64 s[4:5], s42, v80
	v_cndmask_b32_e64 v15, v15, v82, s[8:9]
	v_add_f32_dpp v81, v81, v81 row_mirror row_mask:0xf bank_mask:0xf bound_ctrl:1
	v_mul_f32_e32 v83, 0x4f800000, v43
	v_cmp_gt_f32_e32 vcc, s42, v43
	v_cndmask_b32_e64 v80, v80, v84, s[4:5]
	v_sqrt_f32_e32 v82, v15
	v_fmamk_f32 v81, v81, 0x3c000000, v39
	v_cndmask_b32_e32 v43, v43, v83, vcc
	v_sqrt_f32_e32 v84, v80
	v_mul_f32_e32 v85, 0x4f800000, v81
	v_cmp_gt_f32_e64 s[6:7], s42, v81
	v_sqrt_f32_e32 v83, v43
	v_add_u32_e32 v86, -1, v82
	v_cndmask_b32_e64 v81, v81, v85, s[6:7]
	v_sqrt_f32_e32 v85, v81
	v_add_u32_e32 v87, 1, v82
	v_add_u32_e32 v96, -1, v84
	v_fma_f32 v102, -v86, v82, v15
	v_add_u32_e32 v94, -1, v83
	v_add_u32_e32 v97, 1, v84
	v_fma_f32 v103, -v87, v82, v15
	v_fma_f32 v106, -v96, v84, v80
	v_cmp_ge_f32_e64 s[10:11], 0, v102
	v_add_u32_e32 v95, 1, v83
	v_fma_f32 v104, -v94, v83, v43
	v_fma_f32 v107, -v97, v84, v80
	v_cndmask_b32_e64 v82, v82, v86, s[10:11]
	v_cmp_ge_f32_e64 s[12:13], 0, v106
	v_cmp_lt_f32_e64 s[16:17], 0, v103
	v_add_u32_e32 v98, -1, v85
	v_fma_f32 v105, -v95, v83, v43
	v_cmp_ge_f32_e64 s[10:11], 0, v104
	v_cndmask_b32_e64 v84, v84, v96, s[12:13]
	v_cmp_lt_f32_e64 s[12:13], 0, v107
	v_cndmask_b32_e64 v82, v82, v87, s[16:17]
	v_add_u32_e32 v99, 1, v85
	v_fma_f32 v110, -v98, v85, v81
	v_cndmask_b32_e64 v83, v83, v94, s[10:11]
	v_cmp_lt_f32_e64 s[10:11], 0, v105
	v_cndmask_b32_e64 v84, v84, v97, s[12:13]
	v_mul_f32_e32 v86, 0x37800000, v82
	v_fma_f32 v111, -v99, v85, v81
	v_cmp_ge_f32_e64 s[14:15], 0, v110
	v_cndmask_b32_e64 v83, v83, v95, s[10:11]
	v_mul_f32_e32 v94, 0x37800000, v84
	v_cndmask_b32_e64 v82, v82, v86, s[8:9]
	v_cmp_class_f32_e64 s[8:9], v15, v40
	v_cndmask_b32_e64 v85, v85, v98, s[14:15]
	v_cmp_lt_f32_e64 s[14:15], 0, v111
	v_mul_f32_e32 v87, 0x37800000, v83
	v_cndmask_b32_e64 v84, v84, v94, s[4:5]
	v_cmp_class_f32_e64 s[4:5], v80, v40
	v_cndmask_b32_e64 v15, v82, v15, s[8:9]
	v_cndmask_b32_e64 v85, v85, v99, s[14:15]
	v_cndmask_b32_e32 v83, v83, v87, vcc
	v_cmp_class_f32_e32 vcc, v43, v40
	v_cndmask_b32_e64 v94, v84, v80, s[4:5]
	v_div_scale_f32 v80, s[4:5], v15, v15, 1.0
	v_mul_f32_e32 v95, 0x37800000, v85
	v_cndmask_b32_e32 v43, v83, v43, vcc
	v_rcp_f32_e32 v96, v80
	v_cndmask_b32_e64 v85, v85, v95, s[6:7]
	v_cmp_class_f32_e64 s[6:7], v81, v40
	v_div_scale_f32 v83, s[4:5], v43, v43, 1.0
	s_nop 0
	v_cndmask_b32_e64 v81, v85, v81, s[6:7]
	v_div_scale_f32 v85, s[6:7], v94, v94, 1.0
	v_rcp_f32_e32 v97, v83
	v_div_scale_f32 v87, s[8:9], v81, v81, 1.0
	v_rcp_f32_e32 v98, v85
	v_rcp_f32_e32 v99, v87
	v_fma_f32 v102, -v80, v96, 1.0
	v_div_scale_f32 v82, vcc, 1.0, v15, 1.0
	v_fmac_f32_e32 v96, v102, v96
	v_fma_f32 v103, -v83, v97, 1.0
	v_mul_f32_e32 v102, v82, v96
	v_div_scale_f32 v84, s[4:5], 1.0, v43, 1.0
	v_fma_f32 v104, -v85, v98, 1.0
	v_fmac_f32_e32 v97, v103, v97
	v_fma_f32 v106, -v80, v102, v82
	v_div_scale_f32 v86, s[6:7], 1.0, v94, 1.0
	v_fma_f32 v105, -v87, v99, 1.0
	v_fmac_f32_e32 v98, v104, v98
	v_mul_f32_e32 v103, v84, v97
	v_fmac_f32_e32 v102, v106, v96
	v_div_scale_f32 v95, s[8:9], 1.0, v81, 1.0
	v_fmac_f32_e32 v99, v105, v99
	v_mul_f32_e32 v104, v86, v98
	v_fma_f32 v107, -v83, v103, v84
	v_fma_f32 v80, -v80, v102, v82
	v_mul_f32_e32 v105, v95, v99
	v_fma_f32 v110, -v85, v104, v86
	v_fmac_f32_e32 v103, v107, v97
	v_div_fmas_f32 v80, v80, v96, v102
	v_fma_f32 v111, -v87, v105, v95
	v_fmac_f32_e32 v104, v110, v98
	v_fma_f32 v82, -v83, v103, v84
	v_div_fixup_f32 v80, v80, v15, 1.0
	s_mov_b64 vcc, s[4:5]
	v_fmac_f32_e32 v105, v111, v99
	v_fma_f32 v86, -v85, v104, v86
	v_div_fmas_f32 v15, v82, v97, v103
	v_pk_mul_f32 v[44:45], v[44:45], v[80:81] op_sel_hi:[1,0]
	s_mov_b64 vcc, s[6:7]
	v_lshlrev_b32_e32 v37, 16, v49
	v_lshlrev_b32_e32 v36, 16, v48
	v_and_b32_e32 v49, 0xffff0000, v49
	v_and_b32_e32 v48, 0xffff0000, v48
	v_fma_f32 v95, -v87, v105, v95
	v_pk_mul_f32 v[82:83], v[88:89], v[80:81] op_sel_hi:[1,0]
	v_pk_mul_f32 v[84:85], v[90:91], v[80:81] op_sel_hi:[1,0]
	v_pk_mul_f32 v[46:47], v[46:47], v[80:81] op_sel_hi:[1,0]
	v_div_fixup_f32 v80, v15, v43, 1.0
	v_div_fmas_f32 v15, v86, v98, v104
	v_pk_mul_f32 v[44:45], v[16:17], v[44:45]
	s_mov_b64 vcc, s[8:9]
	v_lshlrev_b32_e32 v101, 16, v51
	v_lshlrev_b32_e32 v100, 16, v50
	v_and_b32_e32 v51, 0xffff0000, v51
	v_and_b32_e32 v50, 0xffff0000, v50
	v_pk_mul_f32 v[82:83], v[0:1], v[82:83]
	v_pk_mul_f32 v[84:85], v[4:5], v[84:85]
	v_pk_mul_f32 v[46:47], v[2:3], v[46:47]
	v_pk_mul_f32 v[86:87], v[92:93], v[80:81] op_sel_hi:[1,0]
	v_pk_mul_f32 v[52:53], v[52:53], v[80:81] op_sel_hi:[1,0]
	v_pk_mul_f32 v[56:57], v[56:57], v[80:81] op_sel_hi:[1,0]
	v_pk_mul_f32 v[54:55], v[54:55], v[80:81] op_sel_hi:[1,0]
	v_div_fixup_f32 v80, v15, v94, 1.0
	v_div_fmas_f32 v15, v95, v99, v105
	v_pk_mul_f32 v[44:45], v[44:45], v[48:49]
	v_lshlrev_b32_e32 v109, 16, v61
	v_lshlrev_b32_e32 v108, 16, v60
	v_and_b32_e32 v61, 0xffff0000, v61
	v_and_b32_e32 v60, 0xffff0000, v60
	v_lshlrev_b32_e32 v113, 16, v63
	v_lshlrev_b32_e32 v112, 16, v62
	v_and_b32_e32 v63, 0xffff0000, v63
	v_and_b32_e32 v62, 0xffff0000, v62
	v_pk_mul_f32 v[36:37], v[82:83], v[36:37]
	v_pk_mul_f32 v[48:49], v[84:85], v[100:101]
	v_pk_mul_f32 v[46:47], v[46:47], v[50:51]
	v_pk_mul_f32 v[50:51], v[0:1], v[86:87]
	v_pk_mul_f32 v[52:53], v[16:17], v[52:53]
	v_pk_mul_f32 v[56:57], v[4:5], v[56:57]
	v_pk_mul_f32 v[54:55], v[2:3], v[54:55]
	v_pk_mul_f32 v[58:59], v[58:59], v[80:81] op_sel_hi:[1,0]
	v_pk_mul_f32 v[64:65], v[64:65], v[80:81] op_sel_hi:[1,0]
	v_pk_mul_f32 v[68:69], v[68:69], v[80:81] op_sel_hi:[1,0]
	v_pk_mul_f32 v[66:67], v[66:67], v[80:81] op_sel_hi:[1,0]
	v_div_fixup_f32 v80, v15, v81, 1.0
	v_bfe_u32 v81, v45, 16, 1
	v_lshlrev_b32_e32 v121, 16, v75
	v_lshlrev_b32_e32 v120, 16, v74
	v_bfe_u32 v15, v47, 16, 1
	v_bfe_u32 v43, v46, 16, 1
	v_bfe_u32 v83, v36, 16, 1
	v_bfe_u32 v84, v37, 16, 1
	v_bfe_u32 v85, v48, 16, 1
	v_bfe_u32 v86, v49, 16, 1
	v_pk_mul_f32 v[50:51], v[50:51], v[108:109]
	v_pk_mul_f32 v[52:53], v[52:53], v[60:61]
	v_pk_mul_f32 v[56:57], v[56:57], v[112:113]
	v_pk_mul_f32 v[54:55], v[54:55], v[62:63]
	v_pk_mul_f32 v[58:59], v[0:1], v[58:59]
	v_pk_mul_f32 v[60:61], v[16:17], v[64:65]
	v_pk_mul_f32 v[62:63], v[4:5], v[68:69]
	v_pk_mul_f32 v[64:65], v[2:3], v[66:67]
	v_pk_mul_f32 v[66:67], v[70:71], v[80:81] op_sel_hi:[1,0]
	v_pk_mul_f32 v[70:71], v[76:77], v[80:81] op_sel_hi:[1,0]
	v_lshlrev_b32_e32 v25, 16, v29
	v_lshlrev_b32_e32 v24, 16, v28
	v_and_b32_e32 v27, 0xffff0000, v29
	v_and_b32_e32 v26, 0xffff0000, v28
	v_lshlrev_b32_e32 v29, 16, v31
	v_lshlrev_b32_e32 v28, 16, v30
	v_and_b32_e32 v75, 0xffff0000, v75
	v_and_b32_e32 v74, 0xffff0000, v74
	v_bfe_u32 v82, v44, 16, 1
	v_pk_mul_f32 v[68:69], v[72:73], v[80:81] op_sel_hi:[1,0]
	v_pk_mul_f32 v[72:73], v[78:79], v[80:81] op_sel_hi:[1,0]
	v_add3_u32 v77, v45, v81, s43
	v_add3_u32 v43, v46, v43, s43
	v_add3_u32 v15, v47, v15, s43
	v_add3_u32 v78, v49, v86, s43
	v_add3_u32 v79, v48, v85, s43
	v_add3_u32 v80, v37, v84, s43
	v_add3_u32 v81, v36, v83, s43
	v_bfe_u32 v86, v50, 16, 1
	v_bfe_u32 v87, v51, 16, 1
	v_bfe_u32 v88, v56, 16, 1
	v_bfe_u32 v89, v57, 16, 1
	v_pk_mul_f32 v[32:33], v[58:59], v[32:33]
	v_pk_mul_f32 v[36:37], v[62:63], v[120:121]
	v_pk_mul_f32 v[46:47], v[0:1], v[66:67]
	v_pk_mul_f32 v[58:59], v[4:5], v[70:71]
	v_and_b32_e32 v31, 0xffff0000, v31
	v_and_b32_e32 v30, 0xffff0000, v30
	v_add3_u32 v76, v44, v82, s43
	v_bfe_u32 v82, v55, 16, 1
	v_bfe_u32 v83, v54, 16, 1
	v_bfe_u32 v84, v53, 16, 1
	v_bfe_u32 v85, v52, 16, 1
	v_pk_mul_f32 v[34:35], v[60:61], v[34:35]
	v_pk_mul_f32 v[44:45], v[64:65], v[74:75]
	v_pk_mul_f32 v[48:49], v[16:17], v[68:69]
	v_pk_mul_f32 v[60:61], v[2:3], v[72:73]
	v_lshrrev_b32_e32 v62, 16, v81
	v_lshrrev_b32_e32 v63, 16, v80
	v_lshrrev_b32_e32 v64, 16, v79
	v_lshrrev_b32_e32 v65, 16, v78
	v_add3_u32 v57, v57, v89, s43
	v_add3_u32 v56, v56, v88, s43
	v_add3_u32 v51, v51, v87, s43
	v_add3_u32 v50, v50, v86, s43
	v_bfe_u32 v70, v32, 16, 1
	v_bfe_u32 v71, v33, 16, 1
	v_bfe_u32 v72, v36, 16, 1
	v_bfe_u32 v73, v37, 16, 1
	v_pk_mul_f32 v[46:47], v[46:47], v[24:25]
	v_pk_mul_f32 v[28:29], v[58:59], v[28:29]
	v_add3_u32 v52, v52, v85, s43
	v_add3_u32 v53, v53, v84, s43
	v_add3_u32 v54, v54, v83, s43
	v_add3_u32 v55, v55, v82, s43
	v_bfe_u32 v66, v45, 16, 1
	v_bfe_u32 v67, v44, 16, 1
	v_bfe_u32 v68, v35, 16, 1
	v_bfe_u32 v69, v34, 16, 1
	v_pk_mul_f32 v[48:49], v[48:49], v[26:27]
	v_pk_mul_f32 v[30:31], v[60:61], v[30:31]
	v_and_or_b32 v27, v15, s29, v65
	v_and_or_b32 v26, v43, s29, v64
	v_and_or_b32 v25, v77, s29, v63
	v_and_or_b32 v24, v76, s29, v62
	v_lshrrev_b32_e32 v15, 16, v50
	v_lshrrev_b32_e32 v43, 16, v51
	v_lshrrev_b32_e32 v50, 16, v56
	v_lshrrev_b32_e32 v51, 16, v57
	v_add3_u32 v37, v37, v73, s43
	v_add3_u32 v36, v36, v72, s43
	v_add3_u32 v33, v33, v71, s43
	v_add3_u32 v32, v32, v70, s43
	v_bfe_u32 v60, v46, 16, 1
	v_bfe_u32 v61, v47, 16, 1
	v_bfe_u32 v62, v28, 16, 1
	v_bfe_u32 v63, v29, 16, 1
	global_store_dwordx4 v[22:23], v[24:27], off sc1
	s_nop 1
	v_add3_u32 v34, v34, v69, s43
	v_add3_u32 v35, v35, v68, s43
	v_add3_u32 v44, v44, v67, s43
	v_add3_u32 v45, v45, v66, s43
	v_bfe_u32 v56, v31, 16, 1
	v_bfe_u32 v57, v30, 16, 1
	v_bfe_u32 v58, v49, 16, 1
	v_bfe_u32 v59, v48, 16, 1
	v_and_or_b32 v25, v55, s29, v51
	v_and_or_b32 v24, v54, s29, v50
	v_and_or_b32 v23, v53, s29, v43
	v_and_or_b32 v22, v52, s29, v15
	v_lshrrev_b32_e32 v15, 16, v32
	v_lshrrev_b32_e32 v26, 16, v33
	v_lshrrev_b32_e32 v27, 16, v36
	v_lshrrev_b32_e32 v32, 16, v37
	v_add3_u32 v29, v29, v63, s43
	v_add3_u32 v28, v28, v62, s43
	v_add3_u32 v37, v47, v61, s43
	v_add3_u32 v43, v46, v60, s43
	global_store_dwordx4 v[20:21], v[22:25], off sc1
	s_nop 1
	v_add3_u32 v33, v48, v59, s43
	v_add3_u32 v36, v49, v58, s43
	v_add3_u32 v30, v30, v57, s43
	v_add3_u32 v31, v31, v56, s43
	v_and_or_b32 v23, v45, s29, v32
	v_and_or_b32 v22, v44, s29, v27
	v_and_or_b32 v21, v35, s29, v26
	v_and_or_b32 v20, v34, s29, v15
	v_lshrrev_b32_e32 v15, 16, v43
	v_lshrrev_b32_e32 v24, 16, v37
	v_lshrrev_b32_e32 v25, 16, v28
	v_lshrrev_b32_e32 v26, 16, v29
	global_store_dwordx4 v[18:19], v[20:23], off sc1
	s_nop 1
	v_and_or_b32 v21, v31, s29, v26
	v_and_or_b32 v20, v30, s29, v25
	v_and_or_b32 v19, v36, s29, v24
	v_and_or_b32 v18, v33, s29, v15
	global_store_dwordx4 v[6:7], v[18:21], off sc1
	s_nop 1
	s_waitcnt vmcnt(13)
	v_lshlrev_b32_e32 v208, 16, v152
	v_lshlrev_b32_e32 v209, 16, v153
	s_waitcnt vmcnt(12)
	v_lshlrev_b32_e32 v217, 16, v165
	v_lshlrev_b32_e32 v216, 16, v164
	v_and_b32_e32 v210, 0xffff0000, v152
	v_and_b32_e32 v211, 0xffff0000, v153
	v_lshlrev_b32_e32 v200, 16, v144
	v_lshlrev_b32_e32 v201, 16, v145
	v_lshlrev_b32_e32 v212, 16, v154
	v_and_b32_e32 v214, 0xffff0000, v154
	v_lshlrev_b32_e32 v213, 16, v155
	v_and_b32_e32 v215, 0xffff0000, v155
	v_and_b32_e32 v165, 0xffff0000, v165
	v_and_b32_e32 v164, 0xffff0000, v164
	v_lshlrev_b32_e32 v219, 16, v167
	v_lshlrev_b32_e32 v218, 16, v166
	s_waitcnt vmcnt(10)
	v_lshlrev_b32_e32 v224, 16, v174
	v_and_b32_e32 v174, 0xffff0000, v174
	v_lshlrev_b32_e32 v225, 16, v175
	v_and_b32_e32 v175, 0xffff0000, v175
	s_waitcnt vmcnt(9)
	v_lshlrev_b32_e32 v231, 16, v179
	v_lshlrev_b32_e32 v230, 16, v178
	v_and_b32_e32 v179, 0xffff0000, v179
	v_and_b32_e32 v178, 0xffff0000, v178
	s_waitcnt vmcnt(7)
	v_lshlrev_b32_e32 v234, 16, v184
	v_lshlrev_b32_e32 v235, 16, v185
	v_lshlrev_b32_e32 v236, 16, v186
	v_and_b32_e32 v186, 0xffff0000, v186
	v_lshlrev_b32_e32 v237, 16, v187
	v_and_b32_e32 v187, 0xffff0000, v187
	s_waitcnt vmcnt(6)
	v_lshlrev_b32_e32 v239, 16, v189
	v_lshlrev_b32_e32 v238, 16, v188
	s_waitcnt vmcnt(5)
	v_lshlrev_b32_e32 v153, 16, v193
	v_lshlrev_b32_e32 v152, 16, v192
	v_and_b32_e32 v155, 0xffff0000, v193
	v_and_b32_e32 v154, 0xffff0000, v192
	v_lshlrev_b32_e32 v193, 16, v191
	v_lshlrev_b32_e32 v192, 16, v190
	v_and_b32_e32 v191, 0xffff0000, v191
	v_and_b32_e32 v190, 0xffff0000, v190
	s_waitcnt vmcnt(4)
	v_lshlrev_b32_e32 v243, 16, v197
	v_lshlrev_b32_e32 v242, 16, v196
	v_pk_fma_f32 v[208:209], v[10:11], v[208:209], v[216:217] neg_lo:[1,0,0] neg_hi:[1,0,0]
	v_and_b32_e32 v202, 0xffff0000, v144
	v_and_b32_e32 v203, 0xffff0000, v145
	v_and_b32_e32 v167, 0xffff0000, v167
	v_and_b32_e32 v166, 0xffff0000, v166
	v_lshlrev_b32_e32 v222, 16, v172
	v_lshlrev_b32_e32 v223, 16, v173
	v_lshlrev_b32_e32 v227, 16, v177
	v_lshlrev_b32_e32 v226, 16, v176
	v_and_b32_e32 v184, 0xffff0000, v184
	v_and_b32_e32 v185, 0xffff0000, v185
	v_and_b32_e32 v189, 0xffff0000, v189
	v_and_b32_e32 v188, 0xffff0000, v188
	v_and_b32_e32 v197, 0xffff0000, v197
	v_and_b32_e32 v196, 0xffff0000, v196
	v_pk_fma_f32 v[164:165], v[10:11], v[210:211], v[164:165] neg_lo:[1,0,0] neg_hi:[1,0,0]
	v_pk_fma_f32 v[210:211], v[10:11], v[212:213], v[218:219] neg_lo:[1,0,0] neg_hi:[1,0,0]
	v_pk_fma_f32 v[174:175], v[10:11], v[174:175], v[178:179] neg_lo:[1,0,0] neg_hi:[1,0,0]
	v_pk_fma_f32 v[178:179], v[10:11], v[234:235], v[238:239] neg_lo:[1,0,0] neg_hi:[1,0,0]
	v_pk_fma_f32 v[186:187], v[10:11], v[186:187], v[190:191] neg_lo:[1,0,0] neg_hi:[1,0,0]
	v_pk_fma_f32 v[190:191], v[10:11], v[200:201], v[242:243] neg_lo:[1,0,0] neg_hi:[1,0,0]
	v_pk_mul_f32 v[200:201], v[208:209], v[208:209]
	v_lshlrev_b32_e32 v204, 16, v146
	v_lshlrev_b32_e32 v205, 16, v147
	v_and_b32_e32 v172, 0xffff0000, v172
	v_and_b32_e32 v173, 0xffff0000, v173
	v_and_b32_e32 v177, 0xffff0000, v177
	v_and_b32_e32 v176, 0xffff0000, v176
	v_lshlrev_b32_e32 v245, 16, v199
	v_lshlrev_b32_e32 v244, 16, v198
	v_pk_fma_f32 v[166:167], v[10:11], v[214:215], v[166:167] neg_lo:[1,0,0] neg_hi:[1,0,0]
	v_pk_fma_f32 v[212:213], v[10:11], v[222:223], v[226:227] neg_lo:[1,0,0] neg_hi:[1,0,0]
	v_pk_fma_f32 v[184:185], v[10:11], v[184:185], v[188:189] neg_lo:[1,0,0] neg_hi:[1,0,0]
	v_pk_fma_f32 v[188:189], v[10:11], v[236:237], v[192:193] neg_lo:[1,0,0] neg_hi:[1,0,0]
	v_pk_fma_f32 v[192:193], v[10:11], v[202:203], v[196:197] neg_lo:[1,0,0] neg_hi:[1,0,0]
	v_pk_mul_f32 v[202:203], v[210:211], v[210:211]
	v_pk_mul_f32 v[214:215], v[178:179], v[178:179]
	v_pk_fma_f32 v[200:201], v[164:165], v[164:165], v[200:201]
	v_and_b32_e32 v206, 0xffff0000, v146
	v_and_b32_e32 v207, 0xffff0000, v147
	v_and_b32_e32 v199, 0xffff0000, v199
	v_and_b32_e32 v198, 0xffff0000, v198
	v_pk_fma_f32 v[172:173], v[10:11], v[172:173], v[176:177] neg_lo:[1,0,0] neg_hi:[1,0,0]
	v_pk_fma_f32 v[176:177], v[10:11], v[224:225], v[230:231] neg_lo:[1,0,0] neg_hi:[1,0,0]
	v_pk_fma_f32 v[196:197], v[10:11], v[204:205], v[244:245] neg_lo:[1,0,0] neg_hi:[1,0,0]
	v_pk_mul_f32 v[204:205], v[212:213], v[212:213]
	v_pk_mul_f32 v[216:217], v[188:189], v[188:189]
	v_pk_fma_f32 v[202:203], v[166:167], v[166:167], v[202:203]
	v_pk_fma_f32 v[214:215], v[184:185], v[184:185], v[214:215]
	v_add_f32_e32 v135, v200, v201
	v_pk_fma_f32 v[198:199], v[10:11], v[206:207], v[198:199] neg_lo:[1,0,0] neg_hi:[1,0,0]
	v_pk_mul_f32 v[206:207], v[176:177], v[176:177]
	v_pk_fma_f32 v[204:205], v[172:173], v[172:173], v[204:205]
	v_pk_fma_f32 v[216:217], v[186:187], v[186:187], v[216:217]
	v_add_f32_e32 v200, v214, v215
	v_add_f32_e32 v135, v202, v135
	v_pk_mul_f32 v[218:219], v[190:191], v[190:191]
	v_pk_fma_f32 v[206:207], v[174:175], v[174:175], v[206:207]
	v_add_f32_e32 v163, v204, v205
	v_add_f32_e32 v200, v216, v200
	v_add_f32_e32 v135, v203, v135
	v_pk_mul_f32 v[222:223], v[196:197], v[196:197]
	v_pk_fma_f32 v[218:219], v[192:193], v[192:193], v[218:219]
	v_add_f32_e32 v163, v206, v163
	v_add_f32_e32 v200, v217, v200
	v_add_f32_dpp v135, v135, v135 quad_perm:[1,0,3,2] row_mask:0xf bank_mask:0xf bound_ctrl:1
	v_pk_fma_f32 v[222:223], v[198:199], v[198:199], v[222:223]
	v_add_f32_e32 v201, v218, v219
	v_add_f32_e32 v163, v207, v163
	v_add_f32_dpp v200, v200, v200 quad_perm:[1,0,3,2] row_mask:0xf bank_mask:0xf bound_ctrl:1
	v_add_f32_dpp v135, v135, v135 quad_perm:[2,3,0,1] row_mask:0xf bank_mask:0xf bound_ctrl:1
	v_add_f32_e32 v201, v222, v201
	v_add_f32_dpp v163, v163, v163 quad_perm:[1,0,3,2] row_mask:0xf bank_mask:0xf bound_ctrl:1
	v_add_f32_dpp v200, v200, v200 quad_perm:[2,3,0,1] row_mask:0xf bank_mask:0xf bound_ctrl:1
	v_add_f32_dpp v135, v135, v135 row_half_mirror row_mask:0xf bank_mask:0xf bound_ctrl:1
	v_add_f32_e32 v201, v223, v201
	v_add_f32_dpp v163, v163, v163 quad_perm:[2,3,0,1] row_mask:0xf bank_mask:0xf bound_ctrl:1
	v_add_f32_dpp v200, v200, v200 row_half_mirror row_mask:0xf bank_mask:0xf bound_ctrl:1
	v_add_f32_dpp v135, v135, v135 row_mirror row_mask:0xf bank_mask:0xf bound_ctrl:1
	v_add_f32_dpp v201, v201, v201 quad_perm:[1,0,3,2] row_mask:0xf bank_mask:0xf bound_ctrl:1
	v_add_f32_dpp v163, v163, v163 row_half_mirror row_mask:0xf bank_mask:0xf bound_ctrl:1
	v_add_f32_dpp v200, v200, v200 row_mirror row_mask:0xf bank_mask:0xf bound_ctrl:1
	v_fmamk_f32 v135, v135, 0x3c000000, v39
	v_add_f32_dpp v201, v201, v201 quad_perm:[2,3,0,1] row_mask:0xf bank_mask:0xf bound_ctrl:1
	v_add_f32_dpp v163, v163, v163 row_mirror row_mask:0xf bank_mask:0xf bound_ctrl:1
	v_fmamk_f32 v200, v200, 0x3c000000, v39
	v_mul_f32_e32 v202, 0x4f800000, v135
	v_cmp_gt_f32_e64 s[8:9], s42, v135
	v_add_f32_dpp v201, v201, v201 row_half_mirror row_mask:0xf bank_mask:0xf bound_ctrl:1
	v_fmamk_f32 v163, v163, 0x3c000000, v39
	v_mul_f32_e32 v204, 0x4f800000, v200
	v_cmp_gt_f32_e64 s[4:5], s42, v200
	v_cndmask_b32_e64 v135, v135, v202, s[8:9]
	v_add_f32_dpp v201, v201, v201 row_mirror row_mask:0xf bank_mask:0xf bound_ctrl:1
	v_mul_f32_e32 v203, 0x4f800000, v163
	v_cmp_gt_f32_e32 vcc, s42, v163
	v_cndmask_b32_e64 v200, v200, v204, s[4:5]
	v_sqrt_f32_e32 v202, v135
	v_fmamk_f32 v201, v201, 0x3c000000, v39
	v_cndmask_b32_e32 v163, v163, v203, vcc
	v_sqrt_f32_e32 v204, v200
	v_mul_f32_e32 v205, 0x4f800000, v201
	v_cmp_gt_f32_e64 s[6:7], s42, v201
	v_sqrt_f32_e32 v203, v163
	v_add_u32_e32 v206, -1, v202
	v_cndmask_b32_e64 v201, v201, v205, s[6:7]
	v_sqrt_f32_e32 v205, v201
	v_add_u32_e32 v207, 1, v202
	v_add_u32_e32 v216, -1, v204
	v_fma_f32 v222, -v206, v202, v135
	v_add_u32_e32 v214, -1, v203
	v_add_u32_e32 v217, 1, v204
	v_fma_f32 v223, -v207, v202, v135
	v_fma_f32 v226, -v216, v204, v200
	v_cmp_ge_f32_e64 s[10:11], 0, v222
	v_add_u32_e32 v215, 1, v203
	v_fma_f32 v224, -v214, v203, v163
	v_fma_f32 v227, -v217, v204, v200
	v_cndmask_b32_e64 v202, v202, v206, s[10:11]
	v_cmp_ge_f32_e64 s[12:13], 0, v226
	v_cmp_lt_f32_e64 s[16:17], 0, v223
	v_add_u32_e32 v218, -1, v205
	v_fma_f32 v225, -v215, v203, v163
	v_cmp_ge_f32_e64 s[10:11], 0, v224
	v_cndmask_b32_e64 v204, v204, v216, s[12:13]
	v_cmp_lt_f32_e64 s[12:13], 0, v227
	v_cndmask_b32_e64 v202, v202, v207, s[16:17]
	v_add_u32_e32 v219, 1, v205
	v_fma_f32 v230, -v218, v205, v201
	v_cndmask_b32_e64 v203, v203, v214, s[10:11]
	v_cmp_lt_f32_e64 s[10:11], 0, v225
	v_cndmask_b32_e64 v204, v204, v217, s[12:13]
	v_mul_f32_e32 v206, 0x37800000, v202
	v_fma_f32 v231, -v219, v205, v201
	v_cmp_ge_f32_e64 s[14:15], 0, v230
	v_cndmask_b32_e64 v203, v203, v215, s[10:11]
	v_mul_f32_e32 v214, 0x37800000, v204
	v_cndmask_b32_e64 v202, v202, v206, s[8:9]
	v_cmp_class_f32_e64 s[8:9], v135, v40
	v_cndmask_b32_e64 v205, v205, v218, s[14:15]
	v_cmp_lt_f32_e64 s[14:15], 0, v231
	v_mul_f32_e32 v207, 0x37800000, v203
	v_cndmask_b32_e64 v204, v204, v214, s[4:5]
	v_cmp_class_f32_e64 s[4:5], v200, v40
	v_cndmask_b32_e64 v135, v202, v135, s[8:9]
	v_cndmask_b32_e64 v205, v205, v219, s[14:15]
	v_cndmask_b32_e32 v203, v203, v207, vcc
	v_cmp_class_f32_e32 vcc, v163, v40
	v_cndmask_b32_e64 v214, v204, v200, s[4:5]
	v_div_scale_f32 v200, s[4:5], v135, v135, 1.0
	v_mul_f32_e32 v215, 0x37800000, v205
	v_cndmask_b32_e32 v163, v203, v163, vcc
	v_rcp_f32_e32 v216, v200
	v_cndmask_b32_e64 v205, v205, v215, s[6:7]
	v_cmp_class_f32_e64 s[6:7], v201, v40
	v_div_scale_f32 v203, s[4:5], v163, v163, 1.0
	s_nop 0
	v_cndmask_b32_e64 v201, v205, v201, s[6:7]
	v_div_scale_f32 v205, s[6:7], v214, v214, 1.0
	v_rcp_f32_e32 v217, v203
	v_div_scale_f32 v207, s[8:9], v201, v201, 1.0
	v_rcp_f32_e32 v218, v205
	v_rcp_f32_e32 v219, v207
	v_fma_f32 v222, -v200, v216, 1.0
	v_div_scale_f32 v202, vcc, 1.0, v135, 1.0
	v_fmac_f32_e32 v216, v222, v216
	v_fma_f32 v223, -v203, v217, 1.0
	v_mul_f32_e32 v222, v202, v216
	v_div_scale_f32 v204, s[4:5], 1.0, v163, 1.0
	v_fma_f32 v224, -v205, v218, 1.0
	v_fmac_f32_e32 v217, v223, v217
	v_fma_f32 v226, -v200, v222, v202
	v_div_scale_f32 v206, s[6:7], 1.0, v214, 1.0
	v_fma_f32 v225, -v207, v219, 1.0
	v_fmac_f32_e32 v218, v224, v218
	v_mul_f32_e32 v223, v204, v217
	v_fmac_f32_e32 v222, v226, v216
	v_div_scale_f32 v215, s[8:9], 1.0, v201, 1.0
	v_fmac_f32_e32 v219, v225, v219
	v_mul_f32_e32 v224, v206, v218
	v_fma_f32 v227, -v203, v223, v204
	v_fma_f32 v200, -v200, v222, v202
	v_mul_f32_e32 v225, v215, v219
	v_fma_f32 v230, -v205, v224, v206
	v_fmac_f32_e32 v223, v227, v217
	v_div_fmas_f32 v200, v200, v216, v222
	v_fma_f32 v231, -v207, v225, v215
	v_fmac_f32_e32 v224, v230, v218
	v_fma_f32 v202, -v203, v223, v204
	v_div_fixup_f32 v200, v200, v135, 1.0
	s_mov_b64 vcc, s[4:5]
	v_fmac_f32_e32 v225, v231, v219
	v_fma_f32 v206, -v205, v224, v206
	v_div_fmas_f32 v135, v202, v217, v223
	v_pk_mul_f32 v[164:165], v[164:165], v[200:201] op_sel_hi:[1,0]
	s_mov_b64 vcc, s[6:7]
	v_lshlrev_b32_e32 v157, 16, v169
	v_lshlrev_b32_e32 v156, 16, v168
	v_and_b32_e32 v169, 0xffff0000, v169
	v_and_b32_e32 v168, 0xffff0000, v168
	v_fma_f32 v215, -v207, v225, v215
	v_pk_mul_f32 v[202:203], v[208:209], v[200:201] op_sel_hi:[1,0]
	v_pk_mul_f32 v[204:205], v[210:211], v[200:201] op_sel_hi:[1,0]
	v_pk_mul_f32 v[166:167], v[166:167], v[200:201] op_sel_hi:[1,0]
	v_div_fixup_f32 v200, v135, v163, 1.0
	v_div_fmas_f32 v135, v206, v218, v224
	v_pk_mul_f32 v[164:165], v[16:17], v[164:165]
	s_mov_b64 vcc, s[8:9]
	v_lshlrev_b32_e32 v221, 16, v171
	v_lshlrev_b32_e32 v220, 16, v170
	v_and_b32_e32 v171, 0xffff0000, v171
	v_and_b32_e32 v170, 0xffff0000, v170
	v_pk_mul_f32 v[202:203], v[0:1], v[202:203]
	v_pk_mul_f32 v[204:205], v[4:5], v[204:205]
	v_pk_mul_f32 v[166:167], v[2:3], v[166:167]
	v_pk_mul_f32 v[206:207], v[212:213], v[200:201] op_sel_hi:[1,0]
	v_pk_mul_f32 v[172:173], v[172:173], v[200:201] op_sel_hi:[1,0]
	v_pk_mul_f32 v[176:177], v[176:177], v[200:201] op_sel_hi:[1,0]
	v_pk_mul_f32 v[174:175], v[174:175], v[200:201] op_sel_hi:[1,0]
	v_div_fixup_f32 v200, v135, v214, 1.0
	v_div_fmas_f32 v135, v215, v219, v225
	v_pk_mul_f32 v[164:165], v[164:165], v[168:169]
	v_lshlrev_b32_e32 v229, 16, v181
	v_lshlrev_b32_e32 v228, 16, v180
	v_and_b32_e32 v181, 0xffff0000, v181
	v_and_b32_e32 v180, 0xffff0000, v180
	v_lshlrev_b32_e32 v233, 16, v183
	v_lshlrev_b32_e32 v232, 16, v182
	v_and_b32_e32 v183, 0xffff0000, v183
	v_and_b32_e32 v182, 0xffff0000, v182
	v_pk_mul_f32 v[156:157], v[202:203], v[156:157]
	v_pk_mul_f32 v[168:169], v[204:205], v[220:221]
	v_pk_mul_f32 v[166:167], v[166:167], v[170:171]
	v_pk_mul_f32 v[170:171], v[0:1], v[206:207]
	v_pk_mul_f32 v[172:173], v[16:17], v[172:173]
	v_pk_mul_f32 v[176:177], v[4:5], v[176:177]
	v_pk_mul_f32 v[174:175], v[2:3], v[174:175]
	v_pk_mul_f32 v[178:179], v[178:179], v[200:201] op_sel_hi:[1,0]
	v_pk_mul_f32 v[184:185], v[184:185], v[200:201] op_sel_hi:[1,0]
	v_pk_mul_f32 v[188:189], v[188:189], v[200:201] op_sel_hi:[1,0]
	v_pk_mul_f32 v[186:187], v[186:187], v[200:201] op_sel_hi:[1,0]
	v_div_fixup_f32 v200, v135, v201, 1.0
	v_bfe_u32 v201, v165, 16, 1
	v_lshlrev_b32_e32 v241, 16, v195
	v_lshlrev_b32_e32 v240, 16, v194
	v_bfe_u32 v135, v167, 16, 1
	v_bfe_u32 v163, v166, 16, 1
	v_bfe_u32 v203, v156, 16, 1
	v_bfe_u32 v204, v157, 16, 1
	v_bfe_u32 v205, v168, 16, 1
	v_bfe_u32 v206, v169, 16, 1
	v_pk_mul_f32 v[170:171], v[170:171], v[228:229]
	v_pk_mul_f32 v[172:173], v[172:173], v[180:181]
	v_pk_mul_f32 v[176:177], v[176:177], v[232:233]
	v_pk_mul_f32 v[174:175], v[174:175], v[182:183]
	v_pk_mul_f32 v[178:179], v[0:1], v[178:179]
	v_pk_mul_f32 v[180:181], v[16:17], v[184:185]
	v_pk_mul_f32 v[182:183], v[4:5], v[188:189]
	v_pk_mul_f32 v[184:185], v[2:3], v[186:187]
	v_pk_mul_f32 v[186:187], v[190:191], v[200:201] op_sel_hi:[1,0]
	v_pk_mul_f32 v[190:191], v[196:197], v[200:201] op_sel_hi:[1,0]
	v_lshlrev_b32_e32 v145, 16, v149
	v_lshlrev_b32_e32 v144, 16, v148
	v_and_b32_e32 v147, 0xffff0000, v149
	v_and_b32_e32 v146, 0xffff0000, v148
	v_lshlrev_b32_e32 v149, 16, v151
	v_lshlrev_b32_e32 v148, 16, v150
	v_and_b32_e32 v195, 0xffff0000, v195
	v_and_b32_e32 v194, 0xffff0000, v194
	v_bfe_u32 v202, v164, 16, 1
	v_pk_mul_f32 v[188:189], v[192:193], v[200:201] op_sel_hi:[1,0]
	v_pk_mul_f32 v[192:193], v[198:199], v[200:201] op_sel_hi:[1,0]
	v_add3_u32 v197, v165, v201, s43
	v_add3_u32 v163, v166, v163, s43
	v_add3_u32 v135, v167, v135, s43
	v_add3_u32 v198, v169, v206, s43
	v_add3_u32 v199, v168, v205, s43
	v_add3_u32 v200, v157, v204, s43
	v_add3_u32 v201, v156, v203, s43
	v_bfe_u32 v206, v170, 16, 1
	v_bfe_u32 v207, v171, 16, 1
	v_bfe_u32 v208, v176, 16, 1
	v_bfe_u32 v209, v177, 16, 1
	v_pk_mul_f32 v[152:153], v[178:179], v[152:153]
	v_pk_mul_f32 v[156:157], v[182:183], v[240:241]
	v_pk_mul_f32 v[166:167], v[0:1], v[186:187]
	v_pk_mul_f32 v[178:179], v[4:5], v[190:191]
	v_and_b32_e32 v151, 0xffff0000, v151
	v_and_b32_e32 v150, 0xffff0000, v150
	v_add3_u32 v196, v164, v202, s43
	v_bfe_u32 v202, v175, 16, 1
	v_bfe_u32 v203, v174, 16, 1
	v_bfe_u32 v204, v173, 16, 1
	v_bfe_u32 v205, v172, 16, 1
	v_pk_mul_f32 v[154:155], v[180:181], v[154:155]
	v_pk_mul_f32 v[164:165], v[184:185], v[194:195]
	v_pk_mul_f32 v[168:169], v[16:17], v[188:189]
	v_pk_mul_f32 v[180:181], v[2:3], v[192:193]
	v_lshrrev_b32_e32 v182, 16, v201
	v_lshrrev_b32_e32 v183, 16, v200
	v_lshrrev_b32_e32 v184, 16, v199
	v_lshrrev_b32_e32 v185, 16, v198
	v_add3_u32 v177, v177, v209, s43
	v_add3_u32 v176, v176, v208, s43
	v_add3_u32 v171, v171, v207, s43
	v_add3_u32 v170, v170, v206, s43
	v_bfe_u32 v190, v152, 16, 1
	v_bfe_u32 v191, v153, 16, 1
	v_bfe_u32 v192, v156, 16, 1
	v_bfe_u32 v193, v157, 16, 1
	v_pk_mul_f32 v[166:167], v[166:167], v[144:145]
	v_pk_mul_f32 v[148:149], v[178:179], v[148:149]
	v_add3_u32 v172, v172, v205, s43
	v_add3_u32 v173, v173, v204, s43
	v_add3_u32 v174, v174, v203, s43
	v_add3_u32 v175, v175, v202, s43
	v_bfe_u32 v186, v165, 16, 1
	v_bfe_u32 v187, v164, 16, 1
	v_bfe_u32 v188, v155, 16, 1
	v_bfe_u32 v189, v154, 16, 1
	v_pk_mul_f32 v[168:169], v[168:169], v[146:147]
	v_pk_mul_f32 v[150:151], v[180:181], v[150:151]
	v_and_or_b32 v147, v135, s29, v185
	v_and_or_b32 v146, v163, s29, v184
	v_and_or_b32 v145, v197, s29, v183
	v_and_or_b32 v144, v196, s29, v182
	v_lshrrev_b32_e32 v135, 16, v170
	v_lshrrev_b32_e32 v163, 16, v171
	v_lshrrev_b32_e32 v170, 16, v176
	v_lshrrev_b32_e32 v171, 16, v177
	v_add3_u32 v157, v157, v193, s43
	v_add3_u32 v156, v156, v192, s43
	v_add3_u32 v153, v153, v191, s43
	v_add3_u32 v152, v152, v190, s43
	v_bfe_u32 v180, v166, 16, 1
	v_bfe_u32 v181, v167, 16, 1
	v_bfe_u32 v182, v148, 16, 1
	v_bfe_u32 v183, v149, 16, 1

	global_store_dwordx4 v[142:143], v[144:147], off sc1
	s_nop 1

	v_add3_u32 v154, v154, v189, s43
	v_add3_u32 v155, v155, v188, s43
	v_add3_u32 v164, v164, v187, s43
	v_add3_u32 v165, v165, v186, s43
	v_bfe_u32 v176, v151, 16, 1
	v_bfe_u32 v177, v150, 16, 1
	v_bfe_u32 v178, v169, 16, 1
	v_bfe_u32 v179, v168, 16, 1
	v_and_or_b32 v145, v175, s29, v171
	v_and_or_b32 v144, v174, s29, v170
	v_and_or_b32 v143, v173, s29, v163
	v_and_or_b32 v142, v172, s29, v135
	v_lshrrev_b32_e32 v135, 16, v152
	v_lshrrev_b32_e32 v146, 16, v153
	v_lshrrev_b32_e32 v147, 16, v156
	v_lshrrev_b32_e32 v152, 16, v157
	v_add3_u32 v149, v149, v183, s43
	v_add3_u32 v148, v148, v182, s43
	v_add3_u32 v157, v167, v181, s43
	v_add3_u32 v163, v166, v180, s43

	global_store_dwordx4 v[140:141], v[142:145], off sc1
	s_nop 1

	v_add3_u32 v153, v168, v179, s43
	v_add3_u32 v156, v169, v178, s43
	v_add3_u32 v150, v150, v177, s43
	v_add3_u32 v151, v151, v176, s43
	v_and_or_b32 v143, v165, s29, v152
	v_and_or_b32 v142, v164, s29, v147
	v_and_or_b32 v141, v155, s29, v146
	v_and_or_b32 v140, v154, s29, v135
	v_lshrrev_b32_e32 v135, 16, v163
	v_lshrrev_b32_e32 v144, 16, v157
	v_lshrrev_b32_e32 v145, 16, v148
	v_lshrrev_b32_e32 v146, 16, v149

	global_store_dwordx4 v[138:139], v[140:143], off sc1
	s_nop 1

	v_and_or_b32 v141, v151, s29, v146
	v_and_or_b32 v140, v150, s29, v145
	v_and_or_b32 v139, v156, s29, v144
	v_and_or_b32 v138, v153, s29, v135

	global_store_dwordx4 v[126:127], v[138:141], off sc1
	s_nop 1

